# hand-written SwiGLU+H32 epilogue for the gate-up GEMM (paired permlane swaps) on top of w_down streaming + hand-written idle-round quantiser
# speedup vs baseline: 1.0151x; 1.0059x over previous
.LBB0_914:
	v_lshlrev_b32_e32 v204, 2, v161
	s_lshl_b32 s98, s12, 10
	v_add_u32_e32 v204, s98, v204
	v_lshlrev_b32_e32 v205, 2, v1
	s_lshl_b32 s98, s64, 10
	v_add_u32_e32 v205, s98, v205
	global_load_dwordx4 v[180:183], v204, s[28:29]
	global_load_dwordx4 v[184:187], v204, s[28:29] offset:16
	global_load_dwordx4 v[188:191], v204, s[28:29] offset:512
	global_load_dwordx4 v[192:195], v204, s[28:29] offset:528
	global_load_dword v196, v205, s[8:9]
	global_load_dword v198, v205, s[8:9] offset:64
	global_load_dword v200, v205, s[8:9] offset:128
	global_load_dword v202, v205, s[8:9] offset:192
	global_load_dword v236, v205, s[8:9] offset:512
	global_load_dword v238, v205, s[8:9] offset:576
	global_load_dword v240, v205, s[8:9] offset:640
	global_load_dword v242, v205, s[8:9] offset:704
	v_mul_u32_u24_e32 v250, 0x5600, v1
	v_lshl_add_u32 v250, v161, 1, v250
	v_mov_b32_e32 v244, 0xbfb8aa3b
	v_mov_b32_e32 v245, 0xbfb8aa3b
	v_mov_b32_e32 v246, 0x3e3504f3
	v_mov_b32_e32 v247, 0x3e3504f3
	v_mov_b32_e32 v248, 1.0
	v_mov_b32_e32 v249, 1.0
	v_cvt_f32_i32_e32 v134, v134
	v_cvt_f32_i32_e32 v135, v135
	v_cvt_f32_i32_e32 v136, v136
	v_cvt_f32_i32_e32 v137, v137
	v_cvt_f32_i32_e32 v126, v126
	v_cvt_f32_i32_e32 v127, v127
	v_cvt_f32_i32_e32 v128, v128
	v_cvt_f32_i32_e32 v129, v129
	v_cvt_f32_i32_e32 v130, v130
	v_cvt_f32_i32_e32 v131, v131
	v_cvt_f32_i32_e32 v132, v132
	v_cvt_f32_i32_e32 v133, v133
	v_cvt_f32_i32_e32 v122, v122
	v_cvt_f32_i32_e32 v123, v123
	v_cvt_f32_i32_e32 v124, v124
	v_cvt_f32_i32_e32 v125, v125
	v_cvt_f32_i32_e32 v118, v118
	v_cvt_f32_i32_e32 v119, v119
	v_cvt_f32_i32_e32 v120, v120
	v_cvt_f32_i32_e32 v121, v121
	v_cvt_f32_i32_e32 v110, v110
	v_cvt_f32_i32_e32 v111, v111
	v_cvt_f32_i32_e32 v112, v112
	v_cvt_f32_i32_e32 v113, v113
	v_cvt_f32_i32_e32 v114, v114
	v_cvt_f32_i32_e32 v115, v115
	v_cvt_f32_i32_e32 v116, v116
	v_cvt_f32_i32_e32 v117, v117
	v_cvt_f32_i32_e32 v106, v106
	v_cvt_f32_i32_e32 v107, v107
	v_cvt_f32_i32_e32 v108, v108
	v_cvt_f32_i32_e32 v109, v109
	v_cvt_f32_i32_e32 v102, v102
	v_cvt_f32_i32_e32 v103, v103
	v_cvt_f32_i32_e32 v104, v104
	v_cvt_f32_i32_e32 v105, v105
	v_cvt_f32_i32_e32 v94, v94
	v_cvt_f32_i32_e32 v95, v95
	v_cvt_f32_i32_e32 v96, v96
	v_cvt_f32_i32_e32 v97, v97
	v_cvt_f32_i32_e32 v98, v98
	v_cvt_f32_i32_e32 v99, v99
	v_cvt_f32_i32_e32 v100, v100
	v_cvt_f32_i32_e32 v101, v101
	v_cvt_f32_i32_e32 v90, v90
	v_cvt_f32_i32_e32 v91, v91
	v_cvt_f32_i32_e32 v92, v92
	v_cvt_f32_i32_e32 v93, v93
	v_cvt_f32_i32_e32 v86, v86
	v_cvt_f32_i32_e32 v87, v87
	v_cvt_f32_i32_e32 v88, v88
	v_cvt_f32_i32_e32 v89, v89
	v_cvt_f32_i32_e32 v78, v78
	v_cvt_f32_i32_e32 v79, v79
	v_cvt_f32_i32_e32 v80, v80
	v_cvt_f32_i32_e32 v81, v81
	v_cvt_f32_i32_e32 v82, v82
	v_cvt_f32_i32_e32 v83, v83
	v_cvt_f32_i32_e32 v84, v84
	v_cvt_f32_i32_e32 v85, v85
	v_cvt_f32_i32_e32 v74, v74
	v_cvt_f32_i32_e32 v75, v75
	v_cvt_f32_i32_e32 v76, v76
	v_cvt_f32_i32_e32 v77, v77
	v_cvt_f32_i32_e32 v70, v70
	v_cvt_f32_i32_e32 v71, v71
	v_cvt_f32_i32_e32 v72, v72
	v_cvt_f32_i32_e32 v73, v73
	v_cvt_f32_i32_e32 v58, v58
	v_cvt_f32_i32_e32 v59, v59
	v_cvt_f32_i32_e32 v60, v60
	v_cvt_f32_i32_e32 v61, v61
	v_cvt_f32_i32_e32 v66, v66
	v_cvt_f32_i32_e32 v67, v67
	v_cvt_f32_i32_e32 v68, v68
	v_cvt_f32_i32_e32 v69, v69
	v_cvt_f32_i32_e32 v54, v54
	v_cvt_f32_i32_e32 v55, v55
	v_cvt_f32_i32_e32 v56, v56
	v_cvt_f32_i32_e32 v57, v57
	v_cvt_f32_i32_e32 v46, v46
	v_cvt_f32_i32_e32 v47, v47
	v_cvt_f32_i32_e32 v48, v48
	v_cvt_f32_i32_e32 v49, v49
	v_cvt_f32_i32_e32 v38, v38
	v_cvt_f32_i32_e32 v39, v39
	v_cvt_f32_i32_e32 v40, v40
	v_cvt_f32_i32_e32 v41, v41
	v_cvt_f32_i32_e32 v42, v42
	v_cvt_f32_i32_e32 v43, v43
	v_cvt_f32_i32_e32 v44, v44
	v_cvt_f32_i32_e32 v45, v45
	v_cvt_f32_i32_e32 v34, v34
	v_cvt_f32_i32_e32 v35, v35
	v_cvt_f32_i32_e32 v36, v36
	v_cvt_f32_i32_e32 v37, v37
	v_cvt_f32_i32_e32 v30, v30
	v_cvt_f32_i32_e32 v31, v31
	v_cvt_f32_i32_e32 v32, v32
	v_cvt_f32_i32_e32 v33, v33
	v_cvt_f32_i32_e32 v22, v22
	v_cvt_f32_i32_e32 v23, v23
	v_cvt_f32_i32_e32 v24, v24
	v_cvt_f32_i32_e32 v25, v25
	v_cvt_f32_i32_e32 v26, v26
	v_cvt_f32_i32_e32 v27, v27
	v_cvt_f32_i32_e32 v28, v28
	v_cvt_f32_i32_e32 v29, v29
	v_cvt_f32_i32_e32 v18, v18
	v_cvt_f32_i32_e32 v19, v19
	v_cvt_f32_i32_e32 v20, v20
	v_cvt_f32_i32_e32 v21, v21
	v_cvt_f32_i32_e32 v14, v14
	v_cvt_f32_i32_e32 v15, v15
	v_cvt_f32_i32_e32 v16, v16
	v_cvt_f32_i32_e32 v17, v17
	v_cvt_f32_i32_e32 v6, v6
	v_cvt_f32_i32_e32 v7, v7
	v_cvt_f32_i32_e32 v8, v8
	v_cvt_f32_i32_e32 v9, v9
	v_cvt_f32_i32_e32 v10, v10
	v_cvt_f32_i32_e32 v11, v11
	v_cvt_f32_i32_e32 v12, v12
	v_cvt_f32_i32_e32 v13, v13
	v_cvt_f32_i32_e32 v2, v2
	v_cvt_f32_i32_e32 v3, v3
	v_cvt_f32_i32_e32 v4, v4
	v_cvt_f32_i32_e32 v5, v5
	s_waitcnt vmcnt(0)
	s_sub_i32 s98, s73, 9
	s_cmp_gt_u32 s98, 1
	s_cbranch_scc1 .Lpf7_done
	s_lshl_b32 s98, s98, 8
	s_add_i32 s98, s98, s62
	s_lshl_b32 s98, s98, 3
	s_add_i32 s98, s98, s92
	s_mul_i32 s98, s98, 3
	v_lshlrev_b32_e32 v232, 7, v178
	s_cmpk_lt_u32 s98, 0x2b00
	s_cbranch_scc0 .Lpf7_done
	s_lshl_b32 s99, s98, 14
	s_add_u32 s99, s99, 0x2000
	s_add_u32 s100, s48, s99
	s_addc_u32 s101, s49, 0
	global_load_dword v233, v232, s[100:101]
	s_add_i32 s98, s98, 1
	s_cmpk_lt_u32 s98, 0x2b00
	s_cbranch_scc0 .Lpf7_done
	s_lshl_b32 s99, s98, 14
	s_add_u32 s99, s99, 0x2000
	s_add_u32 s100, s48, s99
	s_addc_u32 s101, s49, 0
	global_load_dword v234, v232, s[100:101]
	s_add_i32 s98, s98, 1
	s_cmpk_lt_u32 s98, 0x2b00
	s_cbranch_scc0 .Lpf7_done
	s_lshl_b32 s99, s98, 14
	s_add_u32 s99, s99, 0x2000
	s_add_u32 s100, s48, s99
	s_addc_u32 s101, s49, 0
	global_load_dword v235, v232, s[100:101]
	s_add_i32 s98, s98, 1
.Lpf7_done:
	s_mul_i32 s98, s64, 0x560000
	s_lshl_b32 s99, s12, 8
	s_add_u32 s98, s98, s99
	s_add_u32 s98, s10, s98
	s_addc_u32 s99, s11, 0
	v_pk_mul_f32 v[50:51], v[180:181], v[196:197] op_sel_hi:[1,0]
	v_pk_mul_f32 v[52:53], v[182:183], v[196:197] op_sel_hi:[1,0]
	v_pk_mul_f32 v[62:63], v[184:185], v[196:197] op_sel_hi:[1,0]
	v_pk_mul_f32 v[64:65], v[186:187], v[196:197] op_sel_hi:[1,0]
	v_pk_mul_f32 v[134:135], v[134:135], v[50:51]
	v_pk_mul_f32 v[136:137], v[136:137], v[52:53]
	v_pk_mul_f32 v[126:127], v[126:127], v[62:63]
	v_pk_mul_f32 v[128:129], v[128:129], v[64:65]
	v_pk_mul_f32 v[50:51], v[188:189], v[196:197] op_sel_hi:[1,0]
	v_pk_mul_f32 v[52:53], v[190:191], v[196:197] op_sel_hi:[1,0]
	v_pk_mul_f32 v[62:63], v[192:193], v[196:197] op_sel_hi:[1,0]
	v_pk_mul_f32 v[64:65], v[194:195], v[196:197] op_sel_hi:[1,0]
	v_pk_mul_f32 v[130:131], v[130:131], v[50:51]
	v_pk_mul_f32 v[132:133], v[132:133], v[52:53]
	v_pk_mul_f32 v[122:123], v[122:123], v[62:63]
	v_pk_mul_f32 v[124:125], v[124:125], v[64:65]
	v_pk_mul_f32 v[50:51], v[134:135], v[244:245]
	v_pk_mul_f32 v[52:53], v[136:137], v[244:245]
	v_pk_mul_f32 v[62:63], v[126:127], v[244:245]
	v_pk_mul_f32 v[64:65], v[128:129], v[244:245]
	v_exp_f32_e32 v50, v50
	v_exp_f32_e32 v51, v51
	v_exp_f32_e32 v52, v52
	v_exp_f32_e32 v53, v53
	v_exp_f32_e32 v62, v62
	v_exp_f32_e32 v63, v63
	v_exp_f32_e32 v64, v64
	v_exp_f32_e32 v65, v65
	v_pk_add_f32 v[50:51], v[50:51], v[248:249]
	v_pk_add_f32 v[52:53], v[52:53], v[248:249]
	v_pk_add_f32 v[62:63], v[62:63], v[248:249]
	v_pk_add_f32 v[64:65], v[64:65], v[248:249]
	v_rcp_f32_e32 v50, v50
	v_rcp_f32_e32 v51, v51
	v_rcp_f32_e32 v52, v52
	v_rcp_f32_e32 v53, v53
	v_rcp_f32_e32 v62, v62
	v_rcp_f32_e32 v63, v63
	v_rcp_f32_e32 v64, v64
	v_rcp_f32_e32 v65, v65
	v_pk_mul_f32 v[134:135], v[134:135], v[50:51]
	v_pk_mul_f32 v[136:137], v[136:137], v[52:53]
	v_pk_mul_f32 v[126:127], v[126:127], v[62:63]
	v_pk_mul_f32 v[128:129], v[128:129], v[64:65]
	v_pk_mul_f32 v[134:135], v[130:131], v[134:135]
	v_pk_mul_f32 v[136:137], v[132:133], v[136:137]
	v_pk_mul_f32 v[126:127], v[122:123], v[126:127]
	v_pk_mul_f32 v[128:129], v[124:125], v[128:129]
	v_pk_add_f32 v[134:135], v[134:135], v[134:135] op_sel:[0,1] op_sel_hi:[0,1] neg_hi:[0,1]
	v_pk_add_f32 v[136:137], v[136:137], v[136:137] op_sel:[0,1] op_sel_hi:[0,1] neg_hi:[0,1]
	v_pk_add_f32 v[126:127], v[126:127], v[126:127] op_sel:[0,1] op_sel_hi:[0,1] neg_hi:[0,1]
	v_pk_add_f32 v[128:129], v[128:129], v[128:129] op_sel:[0,1] op_sel_hi:[0,1] neg_hi:[0,1]
	v_pk_add_f32 v[154:155], v[134:135], v[136:137] neg_lo:[0,1] neg_hi:[0,1]
	v_pk_add_f32 v[134:135], v[134:135], v[136:137]
	v_pk_add_f32 v[156:157], v[126:127], v[128:129] neg_lo:[0,1] neg_hi:[0,1]
	v_pk_add_f32 v[126:127], v[126:127], v[128:129]
	v_pk_add_f32 v[172:173], v[134:135], v[126:127] neg_lo:[0,1] neg_hi:[0,1]
	v_pk_add_f32 v[134:135], v[134:135], v[126:127]
	v_pk_add_f32 v[174:175], v[154:155], v[156:157] neg_lo:[0,1] neg_hi:[0,1]
	v_pk_add_f32 v[154:155], v[154:155], v[156:157]
	s_nop 1
	v_permlane16_swap_b32_e32 v134, v135
	v_permlane16_swap_b32_e32 v154, v155
	v_permlane16_swap_b32_e32 v172, v173
	v_permlane16_swap_b32_e32 v174, v175
	v_pk_add_f32 v[134:135], v[134:135], v[134:135] op_sel:[0,1] op_sel_hi:[0,1] neg_hi:[0,1]
	v_pk_add_f32 v[154:155], v[154:155], v[154:155] op_sel:[0,1] op_sel_hi:[0,1] neg_hi:[0,1]
	v_pk_add_f32 v[172:173], v[172:173], v[172:173] op_sel:[0,1] op_sel_hi:[0,1] neg_hi:[0,1]
	v_pk_add_f32 v[174:175], v[174:175], v[174:175] op_sel:[0,1] op_sel_hi:[0,1] neg_hi:[0,1]
	s_nop 0
	v_permlane16_swap_b32_e32 v134, v135
	v_permlane16_swap_b32_e32 v154, v155
	v_permlane16_swap_b32_e32 v172, v173
	v_permlane16_swap_b32_e32 v174, v175
	s_nop 1
	v_permlane32_swap_b32_e32 v134, v135
	v_permlane32_swap_b32_e32 v154, v155
	v_permlane32_swap_b32_e32 v172, v173
	v_permlane32_swap_b32_e32 v174, v175
	v_pk_add_f32 v[134:135], v[134:135], v[134:135] op_sel:[0,1] op_sel_hi:[0,1] neg_hi:[0,1]
	v_pk_add_f32 v[154:155], v[154:155], v[154:155] op_sel:[0,1] op_sel_hi:[0,1] neg_hi:[0,1]
	v_pk_add_f32 v[172:173], v[172:173], v[172:173] op_sel:[0,1] op_sel_hi:[0,1] neg_hi:[0,1]
	v_pk_add_f32 v[174:175], v[174:175], v[174:175] op_sel:[0,1] op_sel_hi:[0,1] neg_hi:[0,1]
	s_nop 0
	v_permlane32_swap_b32_e32 v134, v135
	v_permlane32_swap_b32_e32 v154, v155
	v_permlane32_swap_b32_e32 v172, v173
	v_permlane32_swap_b32_e32 v174, v175
	v_pk_mul_f32 v[134:135], v[134:135], v[246:247]
	v_pk_mul_f32 v[154:155], v[154:155], v[246:247]
	v_pk_mul_f32 v[172:173], v[172:173], v[246:247]
	v_pk_mul_f32 v[174:175], v[174:175], v[246:247]
	v_cvt_pk_bf16_f32 v168, v134, v135
	v_cvt_pk_bf16_f32 v169, v154, v155
	v_cvt_pk_bf16_f32 v170, v172, v173
	v_cvt_pk_bf16_f32 v171, v174, v175
	global_store_dwordx4 v250, v[168:171], s[98:99] nt
	v_pk_mul_f32 v[50:51], v[180:181], v[198:199] op_sel_hi:[1,0]
	v_pk_mul_f32 v[52:53], v[182:183], v[198:199] op_sel_hi:[1,0]
	v_pk_mul_f32 v[62:63], v[184:185], v[198:199] op_sel_hi:[1,0]
	v_pk_mul_f32 v[64:65], v[186:187], v[198:199] op_sel_hi:[1,0]
	v_pk_mul_f32 v[118:119], v[118:119], v[50:51]
	v_pk_mul_f32 v[120:121], v[120:121], v[52:53]
	v_pk_mul_f32 v[110:111], v[110:111], v[62:63]
	v_pk_mul_f32 v[112:113], v[112:113], v[64:65]
	v_pk_mul_f32 v[50:51], v[188:189], v[198:199] op_sel_hi:[1,0]
	v_pk_mul_f32 v[52:53], v[190:191], v[198:199] op_sel_hi:[1,0]
	v_pk_mul_f32 v[62:63], v[192:193], v[198:199] op_sel_hi:[1,0]
	v_pk_mul_f32 v[64:65], v[194:195], v[198:199] op_sel_hi:[1,0]
	v_pk_mul_f32 v[114:115], v[114:115], v[50:51]
	v_pk_mul_f32 v[116:117], v[116:117], v[52:53]
	v_pk_mul_f32 v[106:107], v[106:107], v[62:63]
	v_pk_mul_f32 v[108:109], v[108:109], v[64:65]
	v_pk_mul_f32 v[50:51], v[118:119], v[244:245]
	v_pk_mul_f32 v[52:53], v[120:121], v[244:245]
	v_pk_mul_f32 v[62:63], v[110:111], v[244:245]
	v_pk_mul_f32 v[64:65], v[112:113], v[244:245]
	v_exp_f32_e32 v50, v50
	v_exp_f32_e32 v51, v51
	v_exp_f32_e32 v52, v52
	v_exp_f32_e32 v53, v53
	v_exp_f32_e32 v62, v62
	v_exp_f32_e32 v63, v63
	v_exp_f32_e32 v64, v64
	v_exp_f32_e32 v65, v65
	v_pk_add_f32 v[50:51], v[50:51], v[248:249]
	v_pk_add_f32 v[52:53], v[52:53], v[248:249]
	v_pk_add_f32 v[62:63], v[62:63], v[248:249]
	v_pk_add_f32 v[64:65], v[64:65], v[248:249]
	v_rcp_f32_e32 v50, v50
	v_rcp_f32_e32 v51, v51
	v_rcp_f32_e32 v52, v52
	v_rcp_f32_e32 v53, v53
	v_rcp_f32_e32 v62, v62
	v_rcp_f32_e32 v63, v63
	v_rcp_f32_e32 v64, v64
	v_rcp_f32_e32 v65, v65
	v_pk_mul_f32 v[118:119], v[118:119], v[50:51]
	v_pk_mul_f32 v[120:121], v[120:121], v[52:53]
	v_pk_mul_f32 v[110:111], v[110:111], v[62:63]
	v_pk_mul_f32 v[112:113], v[112:113], v[64:65]
	v_pk_mul_f32 v[118:119], v[114:115], v[118:119]
	v_pk_mul_f32 v[120:121], v[116:117], v[120:121]
	v_pk_mul_f32 v[110:111], v[106:107], v[110:111]
	v_pk_mul_f32 v[112:113], v[108:109], v[112:113]
	v_pk_add_f32 v[118:119], v[118:119], v[118:119] op_sel:[0,1] op_sel_hi:[0,1] neg_hi:[0,1]
	v_pk_add_f32 v[120:121], v[120:121], v[120:121] op_sel:[0,1] op_sel_hi:[0,1] neg_hi:[0,1]
	v_pk_add_f32 v[110:111], v[110:111], v[110:111] op_sel:[0,1] op_sel_hi:[0,1] neg_hi:[0,1]
	v_pk_add_f32 v[112:113], v[112:113], v[112:113] op_sel:[0,1] op_sel_hi:[0,1] neg_hi:[0,1]
	v_pk_add_f32 v[154:155], v[118:119], v[120:121] neg_lo:[0,1] neg_hi:[0,1]
	v_pk_add_f32 v[118:119], v[118:119], v[120:121]
	v_pk_add_f32 v[156:157], v[110:111], v[112:113] neg_lo:[0,1] neg_hi:[0,1]
	v_pk_add_f32 v[110:111], v[110:111], v[112:113]
	v_pk_add_f32 v[172:173], v[118:119], v[110:111] neg_lo:[0,1] neg_hi:[0,1]
	v_pk_add_f32 v[118:119], v[118:119], v[110:111]
	v_pk_add_f32 v[174:175], v[154:155], v[156:157] neg_lo:[0,1] neg_hi:[0,1]
	v_pk_add_f32 v[154:155], v[154:155], v[156:157]
	s_nop 1
	v_permlane16_swap_b32_e32 v118, v119
	v_permlane16_swap_b32_e32 v154, v155
	v_permlane16_swap_b32_e32 v172, v173
	v_permlane16_swap_b32_e32 v174, v175
	v_pk_add_f32 v[118:119], v[118:119], v[118:119] op_sel:[0,1] op_sel_hi:[0,1] neg_hi:[0,1]
	v_pk_add_f32 v[154:155], v[154:155], v[154:155] op_sel:[0,1] op_sel_hi:[0,1] neg_hi:[0,1]
	v_pk_add_f32 v[172:173], v[172:173], v[172:173] op_sel:[0,1] op_sel_hi:[0,1] neg_hi:[0,1]
	v_pk_add_f32 v[174:175], v[174:175], v[174:175] op_sel:[0,1] op_sel_hi:[0,1] neg_hi:[0,1]
	s_nop 0
	v_permlane16_swap_b32_e32 v118, v119
	v_permlane16_swap_b32_e32 v154, v155
	v_permlane16_swap_b32_e32 v172, v173
	v_permlane16_swap_b32_e32 v174, v175
	s_nop 1
	v_permlane32_swap_b32_e32 v118, v119
	v_permlane32_swap_b32_e32 v154, v155
	v_permlane32_swap_b32_e32 v172, v173
	v_permlane32_swap_b32_e32 v174, v175
	v_pk_add_f32 v[118:119], v[118:119], v[118:119] op_sel:[0,1] op_sel_hi:[0,1] neg_hi:[0,1]
	v_pk_add_f32 v[154:155], v[154:155], v[154:155] op_sel:[0,1] op_sel_hi:[0,1] neg_hi:[0,1]
	v_pk_add_f32 v[172:173], v[172:173], v[172:173] op_sel:[0,1] op_sel_hi:[0,1] neg_hi:[0,1]
	v_pk_add_f32 v[174:175], v[174:175], v[174:175] op_sel:[0,1] op_sel_hi:[0,1] neg_hi:[0,1]
	s_nop 0
	v_permlane32_swap_b32_e32 v118, v119
	v_permlane32_swap_b32_e32 v154, v155
	v_permlane32_swap_b32_e32 v172, v173
	v_permlane32_swap_b32_e32 v174, v175
	v_pk_mul_f32 v[118:119], v[118:119], v[246:247]
	v_pk_mul_f32 v[154:155], v[154:155], v[246:247]
	v_pk_mul_f32 v[172:173], v[172:173], v[246:247]
	v_pk_mul_f32 v[174:175], v[174:175], v[246:247]
	v_cvt_pk_bf16_f32 v168, v118, v119
	v_cvt_pk_bf16_f32 v169, v154, v155
	v_cvt_pk_bf16_f32 v170, v172, v173
	v_cvt_pk_bf16_f32 v171, v174, v175
	s_add_u32 s100, s98, 0x56000
	s_addc_u32 s101, s99, 0
	global_store_dwordx4 v250, v[168:171], s[100:101] nt
	v_pk_mul_f32 v[50:51], v[180:181], v[200:201] op_sel_hi:[1,0]
	v_pk_mul_f32 v[52:53], v[182:183], v[200:201] op_sel_hi:[1,0]
	v_pk_mul_f32 v[62:63], v[184:185], v[200:201] op_sel_hi:[1,0]
	v_pk_mul_f32 v[64:65], v[186:187], v[200:201] op_sel_hi:[1,0]
	v_pk_mul_f32 v[102:103], v[102:103], v[50:51]
	v_pk_mul_f32 v[104:105], v[104:105], v[52:53]
	v_pk_mul_f32 v[94:95], v[94:95], v[62:63]
	v_pk_mul_f32 v[96:97], v[96:97], v[64:65]
	v_pk_mul_f32 v[50:51], v[188:189], v[200:201] op_sel_hi:[1,0]
	v_pk_mul_f32 v[52:53], v[190:191], v[200:201] op_sel_hi:[1,0]
	v_pk_mul_f32 v[62:63], v[192:193], v[200:201] op_sel_hi:[1,0]
	v_pk_mul_f32 v[64:65], v[194:195], v[200:201] op_sel_hi:[1,0]
	v_pk_mul_f32 v[98:99], v[98:99], v[50:51]
	v_pk_mul_f32 v[100:101], v[100:101], v[52:53]
	v_pk_mul_f32 v[90:91], v[90:91], v[62:63]
	v_pk_mul_f32 v[92:93], v[92:93], v[64:65]
	v_pk_mul_f32 v[50:51], v[102:103], v[244:245]
	v_pk_mul_f32 v[52:53], v[104:105], v[244:245]
	v_pk_mul_f32 v[62:63], v[94:95], v[244:245]
	v_pk_mul_f32 v[64:65], v[96:97], v[244:245]
	v_exp_f32_e32 v50, v50
	v_exp_f32_e32 v51, v51
	v_exp_f32_e32 v52, v52
	v_exp_f32_e32 v53, v53
	v_exp_f32_e32 v62, v62
	v_exp_f32_e32 v63, v63
	v_exp_f32_e32 v64, v64
	v_exp_f32_e32 v65, v65
	v_pk_add_f32 v[50:51], v[50:51], v[248:249]
	v_pk_add_f32 v[52:53], v[52:53], v[248:249]
	v_pk_add_f32 v[62:63], v[62:63], v[248:249]
	v_pk_add_f32 v[64:65], v[64:65], v[248:249]
	v_rcp_f32_e32 v50, v50
	v_rcp_f32_e32 v51, v51
	v_rcp_f32_e32 v52, v52
	v_rcp_f32_e32 v53, v53
	v_rcp_f32_e32 v62, v62
	v_rcp_f32_e32 v63, v63
	v_rcp_f32_e32 v64, v64
	v_rcp_f32_e32 v65, v65
	v_pk_mul_f32 v[102:103], v[102:103], v[50:51]
	v_pk_mul_f32 v[104:105], v[104:105], v[52:53]
	v_pk_mul_f32 v[94:95], v[94:95], v[62:63]
	v_pk_mul_f32 v[96:97], v[96:97], v[64:65]
	v_pk_mul_f32 v[102:103], v[98:99], v[102:103]
	v_pk_mul_f32 v[104:105], v[100:101], v[104:105]
	v_pk_mul_f32 v[94:95], v[90:91], v[94:95]
	v_pk_mul_f32 v[96:97], v[92:93], v[96:97]
	v_pk_add_f32 v[102:103], v[102:103], v[102:103] op_sel:[0,1] op_sel_hi:[0,1] neg_hi:[0,1]
	v_pk_add_f32 v[104:105], v[104:105], v[104:105] op_sel:[0,1] op_sel_hi:[0,1] neg_hi:[0,1]
	v_pk_add_f32 v[94:95], v[94:95], v[94:95] op_sel:[0,1] op_sel_hi:[0,1] neg_hi:[0,1]
	v_pk_add_f32 v[96:97], v[96:97], v[96:97] op_sel:[0,1] op_sel_hi:[0,1] neg_hi:[0,1]
	v_pk_add_f32 v[154:155], v[102:103], v[104:105] neg_lo:[0,1] neg_hi:[0,1]
	v_pk_add_f32 v[102:103], v[102:103], v[104:105]
	v_pk_add_f32 v[156:157], v[94:95], v[96:97] neg_lo:[0,1] neg_hi:[0,1]
	v_pk_add_f32 v[94:95], v[94:95], v[96:97]
	v_pk_add_f32 v[172:173], v[102:103], v[94:95] neg_lo:[0,1] neg_hi:[0,1]
	v_pk_add_f32 v[102:103], v[102:103], v[94:95]
	v_pk_add_f32 v[174:175], v[154:155], v[156:157] neg_lo:[0,1] neg_hi:[0,1]
	v_pk_add_f32 v[154:155], v[154:155], v[156:157]
	s_nop 1
	v_permlane16_swap_b32_e32 v102, v103
	v_permlane16_swap_b32_e32 v154, v155
	v_permlane16_swap_b32_e32 v172, v173
	v_permlane16_swap_b32_e32 v174, v175
	v_pk_add_f32 v[102:103], v[102:103], v[102:103] op_sel:[0,1] op_sel_hi:[0,1] neg_hi:[0,1]
	v_pk_add_f32 v[154:155], v[154:155], v[154:155] op_sel:[0,1] op_sel_hi:[0,1] neg_hi:[0,1]
	v_pk_add_f32 v[172:173], v[172:173], v[172:173] op_sel:[0,1] op_sel_hi:[0,1] neg_hi:[0,1]
	v_pk_add_f32 v[174:175], v[174:175], v[174:175] op_sel:[0,1] op_sel_hi:[0,1] neg_hi:[0,1]
	s_nop 0
	v_permlane16_swap_b32_e32 v102, v103
	v_permlane16_swap_b32_e32 v154, v155
	v_permlane16_swap_b32_e32 v172, v173
	v_permlane16_swap_b32_e32 v174, v175
	s_nop 1
	v_permlane32_swap_b32_e32 v102, v103
	v_permlane32_swap_b32_e32 v154, v155
	v_permlane32_swap_b32_e32 v172, v173
	v_permlane32_swap_b32_e32 v174, v175
	v_pk_add_f32 v[102:103], v[102:103], v[102:103] op_sel:[0,1] op_sel_hi:[0,1] neg_hi:[0,1]
	v_pk_add_f32 v[154:155], v[154:155], v[154:155] op_sel:[0,1] op_sel_hi:[0,1] neg_hi:[0,1]
	v_pk_add_f32 v[172:173], v[172:173], v[172:173] op_sel:[0,1] op_sel_hi:[0,1] neg_hi:[0,1]
	v_pk_add_f32 v[174:175], v[174:175], v[174:175] op_sel:[0,1] op_sel_hi:[0,1] neg_hi:[0,1]
	s_nop 0
	v_permlane32_swap_b32_e32 v102, v103
	v_permlane32_swap_b32_e32 v154, v155
	v_permlane32_swap_b32_e32 v172, v173
	v_permlane32_swap_b32_e32 v174, v175
	v_pk_mul_f32 v[102:103], v[102:103], v[246:247]
	v_pk_mul_f32 v[154:155], v[154:155], v[246:247]
	v_pk_mul_f32 v[172:173], v[172:173], v[246:247]
	v_pk_mul_f32 v[174:175], v[174:175], v[246:247]
	v_cvt_pk_bf16_f32 v168, v102, v103
	v_cvt_pk_bf16_f32 v169, v154, v155
	v_cvt_pk_bf16_f32 v170, v172, v173
	v_cvt_pk_bf16_f32 v171, v174, v175
	s_add_u32 s100, s98, 0xac000
	s_addc_u32 s101, s99, 0
	global_store_dwordx4 v250, v[168:171], s[100:101] nt
	v_pk_mul_f32 v[50:51], v[180:181], v[202:203] op_sel_hi:[1,0]
	v_pk_mul_f32 v[52:53], v[182:183], v[202:203] op_sel_hi:[1,0]
	v_pk_mul_f32 v[62:63], v[184:185], v[202:203] op_sel_hi:[1,0]
	v_pk_mul_f32 v[64:65], v[186:187], v[202:203] op_sel_hi:[1,0]
	v_pk_mul_f32 v[86:87], v[86:87], v[50:51]
	v_pk_mul_f32 v[88:89], v[88:89], v[52:53]
	v_pk_mul_f32 v[78:79], v[78:79], v[62:63]
	v_pk_mul_f32 v[80:81], v[80:81], v[64:65]
	v_pk_mul_f32 v[50:51], v[188:189], v[202:203] op_sel_hi:[1,0]
	v_pk_mul_f32 v[52:53], v[190:191], v[202:203] op_sel_hi:[1,0]
	v_pk_mul_f32 v[62:63], v[192:193], v[202:203] op_sel_hi:[1,0]
	v_pk_mul_f32 v[64:65], v[194:195], v[202:203] op_sel_hi:[1,0]
	v_pk_mul_f32 v[82:83], v[82:83], v[50:51]
	v_pk_mul_f32 v[84:85], v[84:85], v[52:53]
	v_pk_mul_f32 v[74:75], v[74:75], v[62:63]
	v_pk_mul_f32 v[76:77], v[76:77], v[64:65]
	v_pk_mul_f32 v[50:51], v[86:87], v[244:245]
	v_pk_mul_f32 v[52:53], v[88:89], v[244:245]
	v_pk_mul_f32 v[62:63], v[78:79], v[244:245]
	v_pk_mul_f32 v[64:65], v[80:81], v[244:245]
	v_exp_f32_e32 v50, v50
	v_exp_f32_e32 v51, v51
	v_exp_f32_e32 v52, v52
	v_exp_f32_e32 v53, v53
	v_exp_f32_e32 v62, v62
	v_exp_f32_e32 v63, v63
	v_exp_f32_e32 v64, v64
	v_exp_f32_e32 v65, v65
	v_pk_add_f32 v[50:51], v[50:51], v[248:249]
	v_pk_add_f32 v[52:53], v[52:53], v[248:249]
	v_pk_add_f32 v[62:63], v[62:63], v[248:249]
	v_pk_add_f32 v[64:65], v[64:65], v[248:249]
	v_rcp_f32_e32 v50, v50
	v_rcp_f32_e32 v51, v51
	v_rcp_f32_e32 v52, v52
	v_rcp_f32_e32 v53, v53
	v_rcp_f32_e32 v62, v62
	v_rcp_f32_e32 v63, v63
	v_rcp_f32_e32 v64, v64
	v_rcp_f32_e32 v65, v65
	v_pk_mul_f32 v[86:87], v[86:87], v[50:51]
	v_pk_mul_f32 v[88:89], v[88:89], v[52:53]
	v_pk_mul_f32 v[78:79], v[78:79], v[62:63]
	v_pk_mul_f32 v[80:81], v[80:81], v[64:65]
	v_pk_mul_f32 v[86:87], v[82:83], v[86:87]
	v_pk_mul_f32 v[88:89], v[84:85], v[88:89]
	v_pk_mul_f32 v[78:79], v[74:75], v[78:79]
	v_pk_mul_f32 v[80:81], v[76:77], v[80:81]
	v_pk_add_f32 v[86:87], v[86:87], v[86:87] op_sel:[0,1] op_sel_hi:[0,1] neg_hi:[0,1]
	v_pk_add_f32 v[88:89], v[88:89], v[88:89] op_sel:[0,1] op_sel_hi:[0,1] neg_hi:[0,1]
	v_pk_add_f32 v[78:79], v[78:79], v[78:79] op_sel:[0,1] op_sel_hi:[0,1] neg_hi:[0,1]
	v_pk_add_f32 v[80:81], v[80:81], v[80:81] op_sel:[0,1] op_sel_hi:[0,1] neg_hi:[0,1]
	v_pk_add_f32 v[154:155], v[86:87], v[88:89] neg_lo:[0,1] neg_hi:[0,1]
	v_pk_add_f32 v[86:87], v[86:87], v[88:89]
	v_pk_add_f32 v[156:157], v[78:79], v[80:81] neg_lo:[0,1] neg_hi:[0,1]
	v_pk_add_f32 v[78:79], v[78:79], v[80:81]
	v_pk_add_f32 v[172:173], v[86:87], v[78:79] neg_lo:[0,1] neg_hi:[0,1]
	v_pk_add_f32 v[86:87], v[86:87], v[78:79]
	v_pk_add_f32 v[174:175], v[154:155], v[156:157] neg_lo:[0,1] neg_hi:[0,1]
	v_pk_add_f32 v[154:155], v[154:155], v[156:157]
	s_nop 1
	v_permlane16_swap_b32_e32 v86, v87
	v_permlane16_swap_b32_e32 v154, v155
	v_permlane16_swap_b32_e32 v172, v173
	v_permlane16_swap_b32_e32 v174, v175
	v_pk_add_f32 v[86:87], v[86:87], v[86:87] op_sel:[0,1] op_sel_hi:[0,1] neg_hi:[0,1]
	v_pk_add_f32 v[154:155], v[154:155], v[154:155] op_sel:[0,1] op_sel_hi:[0,1] neg_hi:[0,1]
	v_pk_add_f32 v[172:173], v[172:173], v[172:173] op_sel:[0,1] op_sel_hi:[0,1] neg_hi:[0,1]
	v_pk_add_f32 v[174:175], v[174:175], v[174:175] op_sel:[0,1] op_sel_hi:[0,1] neg_hi:[0,1]
	s_nop 0
	v_permlane16_swap_b32_e32 v86, v87
	v_permlane16_swap_b32_e32 v154, v155
	v_permlane16_swap_b32_e32 v172, v173
	v_permlane16_swap_b32_e32 v174, v175
	s_nop 1
	v_permlane32_swap_b32_e32 v86, v87
	v_permlane32_swap_b32_e32 v154, v155
	v_permlane32_swap_b32_e32 v172, v173
	v_permlane32_swap_b32_e32 v174, v175
	v_pk_add_f32 v[86:87], v[86:87], v[86:87] op_sel:[0,1] op_sel_hi:[0,1] neg_hi:[0,1]
	v_pk_add_f32 v[154:155], v[154:155], v[154:155] op_sel:[0,1] op_sel_hi:[0,1] neg_hi:[0,1]
	v_pk_add_f32 v[172:173], v[172:173], v[172:173] op_sel:[0,1] op_sel_hi:[0,1] neg_hi:[0,1]
	v_pk_add_f32 v[174:175], v[174:175], v[174:175] op_sel:[0,1] op_sel_hi:[0,1] neg_hi:[0,1]
	s_nop 0
	v_permlane32_swap_b32_e32 v86, v87
	v_permlane32_swap_b32_e32 v154, v155
	v_permlane32_swap_b32_e32 v172, v173
	v_permlane32_swap_b32_e32 v174, v175
	v_pk_mul_f32 v[86:87], v[86:87], v[246:247]
	v_pk_mul_f32 v[154:155], v[154:155], v[246:247]
	v_pk_mul_f32 v[172:173], v[172:173], v[246:247]
	v_pk_mul_f32 v[174:175], v[174:175], v[246:247]
	v_cvt_pk_bf16_f32 v168, v86, v87
	v_cvt_pk_bf16_f32 v169, v154, v155
	v_cvt_pk_bf16_f32 v170, v172, v173
	v_cvt_pk_bf16_f32 v171, v174, v175
	s_add_u32 s100, s98, 0x102000
	s_addc_u32 s101, s99, 0
	global_store_dwordx4 v250, v[168:171], s[100:101] nt
	v_pk_mul_f32 v[50:51], v[180:181], v[236:237] op_sel_hi:[1,0]
	v_pk_mul_f32 v[52:53], v[182:183], v[236:237] op_sel_hi:[1,0]
	v_pk_mul_f32 v[62:63], v[184:185], v[236:237] op_sel_hi:[1,0]
	v_pk_mul_f32 v[64:65], v[186:187], v[236:237] op_sel_hi:[1,0]
	v_pk_mul_f32 v[70:71], v[70:71], v[50:51]
	v_pk_mul_f32 v[72:73], v[72:73], v[52:53]
	v_pk_mul_f32 v[58:59], v[58:59], v[62:63]
	v_pk_mul_f32 v[60:61], v[60:61], v[64:65]
	v_pk_mul_f32 v[50:51], v[188:189], v[236:237] op_sel_hi:[1,0]
	v_pk_mul_f32 v[52:53], v[190:191], v[236:237] op_sel_hi:[1,0]
	v_pk_mul_f32 v[62:63], v[192:193], v[236:237] op_sel_hi:[1,0]
	v_pk_mul_f32 v[64:65], v[194:195], v[236:237] op_sel_hi:[1,0]
	v_pk_mul_f32 v[66:67], v[66:67], v[50:51]
	v_pk_mul_f32 v[68:69], v[68:69], v[52:53]
	v_pk_mul_f32 v[54:55], v[54:55], v[62:63]
	v_pk_mul_f32 v[56:57], v[56:57], v[64:65]
	v_pk_mul_f32 v[50:51], v[70:71], v[244:245]
	v_pk_mul_f32 v[52:53], v[72:73], v[244:245]
	v_pk_mul_f32 v[62:63], v[58:59], v[244:245]
	v_pk_mul_f32 v[64:65], v[60:61], v[244:245]
	v_exp_f32_e32 v50, v50
	v_exp_f32_e32 v51, v51
	v_exp_f32_e32 v52, v52
	v_exp_f32_e32 v53, v53
	v_exp_f32_e32 v62, v62
	v_exp_f32_e32 v63, v63
	v_exp_f32_e32 v64, v64
	v_exp_f32_e32 v65, v65
	v_pk_add_f32 v[50:51], v[50:51], v[248:249]
	v_pk_add_f32 v[52:53], v[52:53], v[248:249]
	v_pk_add_f32 v[62:63], v[62:63], v[248:249]
	v_pk_add_f32 v[64:65], v[64:65], v[248:249]
	v_rcp_f32_e32 v50, v50
	v_rcp_f32_e32 v51, v51
	v_rcp_f32_e32 v52, v52
	v_rcp_f32_e32 v53, v53
	v_rcp_f32_e32 v62, v62
	v_rcp_f32_e32 v63, v63
	v_rcp_f32_e32 v64, v64
	v_rcp_f32_e32 v65, v65
	v_pk_mul_f32 v[70:71], v[70:71], v[50:51]
	v_pk_mul_f32 v[72:73], v[72:73], v[52:53]
	v_pk_mul_f32 v[58:59], v[58:59], v[62:63]
	v_pk_mul_f32 v[60:61], v[60:61], v[64:65]
	v_pk_mul_f32 v[70:71], v[66:67], v[70:71]
	v_pk_mul_f32 v[72:73], v[68:69], v[72:73]
	v_pk_mul_f32 v[58:59], v[54:55], v[58:59]
	v_pk_mul_f32 v[60:61], v[56:57], v[60:61]
	v_pk_add_f32 v[70:71], v[70:71], v[70:71] op_sel:[0,1] op_sel_hi:[0,1] neg_hi:[0,1]
	v_pk_add_f32 v[72:73], v[72:73], v[72:73] op_sel:[0,1] op_sel_hi:[0,1] neg_hi:[0,1]
	v_pk_add_f32 v[58:59], v[58:59], v[58:59] op_sel:[0,1] op_sel_hi:[0,1] neg_hi:[0,1]
	v_pk_add_f32 v[60:61], v[60:61], v[60:61] op_sel:[0,1] op_sel_hi:[0,1] neg_hi:[0,1]
	v_pk_add_f32 v[154:155], v[70:71], v[72:73] neg_lo:[0,1] neg_hi:[0,1]
	v_pk_add_f32 v[70:71], v[70:71], v[72:73]
	v_pk_add_f32 v[156:157], v[58:59], v[60:61] neg_lo:[0,1] neg_hi:[0,1]
	v_pk_add_f32 v[58:59], v[58:59], v[60:61]
	v_pk_add_f32 v[172:173], v[70:71], v[58:59] neg_lo:[0,1] neg_hi:[0,1]
	v_pk_add_f32 v[70:71], v[70:71], v[58:59]
	v_pk_add_f32 v[174:175], v[154:155], v[156:157] neg_lo:[0,1] neg_hi:[0,1]
	v_pk_add_f32 v[154:155], v[154:155], v[156:157]
	s_nop 1
	v_permlane16_swap_b32_e32 v70, v71
	v_permlane16_swap_b32_e32 v154, v155
	v_permlane16_swap_b32_e32 v172, v173
	v_permlane16_swap_b32_e32 v174, v175
	v_pk_add_f32 v[70:71], v[70:71], v[70:71] op_sel:[0,1] op_sel_hi:[0,1] neg_hi:[0,1]
	v_pk_add_f32 v[154:155], v[154:155], v[154:155] op_sel:[0,1] op_sel_hi:[0,1] neg_hi:[0,1]
	v_pk_add_f32 v[172:173], v[172:173], v[172:173] op_sel:[0,1] op_sel_hi:[0,1] neg_hi:[0,1]
	v_pk_add_f32 v[174:175], v[174:175], v[174:175] op_sel:[0,1] op_sel_hi:[0,1] neg_hi:[0,1]
	s_nop 0
	v_permlane16_swap_b32_e32 v70, v71
	v_permlane16_swap_b32_e32 v154, v155
	v_permlane16_swap_b32_e32 v172, v173
	v_permlane16_swap_b32_e32 v174, v175
	s_nop 1
	v_permlane32_swap_b32_e32 v70, v71
	v_permlane32_swap_b32_e32 v154, v155
	v_permlane32_swap_b32_e32 v172, v173
	v_permlane32_swap_b32_e32 v174, v175
	v_pk_add_f32 v[70:71], v[70:71], v[70:71] op_sel:[0,1] op_sel_hi:[0,1] neg_hi:[0,1]
	v_pk_add_f32 v[154:155], v[154:155], v[154:155] op_sel:[0,1] op_sel_hi:[0,1] neg_hi:[0,1]
	v_pk_add_f32 v[172:173], v[172:173], v[172:173] op_sel:[0,1] op_sel_hi:[0,1] neg_hi:[0,1]
	v_pk_add_f32 v[174:175], v[174:175], v[174:175] op_sel:[0,1] op_sel_hi:[0,1] neg_hi:[0,1]
	s_nop 0
	v_permlane32_swap_b32_e32 v70, v71
	v_permlane32_swap_b32_e32 v154, v155
	v_permlane32_swap_b32_e32 v172, v173
	v_permlane32_swap_b32_e32 v174, v175
	v_pk_mul_f32 v[70:71], v[70:71], v[246:247]
	v_pk_mul_f32 v[154:155], v[154:155], v[246:247]
	v_pk_mul_f32 v[172:173], v[172:173], v[246:247]
	v_pk_mul_f32 v[174:175], v[174:175], v[246:247]
	v_cvt_pk_bf16_f32 v168, v70, v71
	v_cvt_pk_bf16_f32 v169, v154, v155
	v_cvt_pk_bf16_f32 v170, v172, v173
	v_cvt_pk_bf16_f32 v171, v174, v175
	s_add_u32 s100, s98, 0x2b0000
	s_addc_u32 s101, s99, 0
	global_store_dwordx4 v250, v[168:171], s[100:101] nt
	v_pk_mul_f32 v[50:51], v[180:181], v[238:239] op_sel_hi:[1,0]
	v_pk_mul_f32 v[52:53], v[182:183], v[238:239] op_sel_hi:[1,0]
	v_pk_mul_f32 v[62:63], v[184:185], v[238:239] op_sel_hi:[1,0]
	v_pk_mul_f32 v[64:65], v[186:187], v[238:239] op_sel_hi:[1,0]
	v_pk_mul_f32 v[46:47], v[46:47], v[50:51]
	v_pk_mul_f32 v[48:49], v[48:49], v[52:53]
	v_pk_mul_f32 v[38:39], v[38:39], v[62:63]
	v_pk_mul_f32 v[40:41], v[40:41], v[64:65]
	v_pk_mul_f32 v[50:51], v[188:189], v[238:239] op_sel_hi:[1,0]
	v_pk_mul_f32 v[52:53], v[190:191], v[238:239] op_sel_hi:[1,0]
	v_pk_mul_f32 v[62:63], v[192:193], v[238:239] op_sel_hi:[1,0]
	v_pk_mul_f32 v[64:65], v[194:195], v[238:239] op_sel_hi:[1,0]
	v_pk_mul_f32 v[42:43], v[42:43], v[50:51]
	v_pk_mul_f32 v[44:45], v[44:45], v[52:53]
	v_pk_mul_f32 v[34:35], v[34:35], v[62:63]
	v_pk_mul_f32 v[36:37], v[36:37], v[64:65]
	v_pk_mul_f32 v[50:51], v[46:47], v[244:245]
	v_pk_mul_f32 v[52:53], v[48:49], v[244:245]
	v_pk_mul_f32 v[62:63], v[38:39], v[244:245]
	v_pk_mul_f32 v[64:65], v[40:41], v[244:245]
	v_exp_f32_e32 v50, v50
	v_exp_f32_e32 v51, v51
	v_exp_f32_e32 v52, v52
	v_exp_f32_e32 v53, v53
	v_exp_f32_e32 v62, v62
	v_exp_f32_e32 v63, v63
	v_exp_f32_e32 v64, v64
	v_exp_f32_e32 v65, v65
	v_pk_add_f32 v[50:51], v[50:51], v[248:249]
	v_pk_add_f32 v[52:53], v[52:53], v[248:249]
	v_pk_add_f32 v[62:63], v[62:63], v[248:249]
	v_pk_add_f32 v[64:65], v[64:65], v[248:249]
	v_rcp_f32_e32 v50, v50
	v_rcp_f32_e32 v51, v51
	v_rcp_f32_e32 v52, v52
	v_rcp_f32_e32 v53, v53
	v_rcp_f32_e32 v62, v62
	v_rcp_f32_e32 v63, v63
	v_rcp_f32_e32 v64, v64
	v_rcp_f32_e32 v65, v65
	v_pk_mul_f32 v[46:47], v[46:47], v[50:51]
	v_pk_mul_f32 v[48:49], v[48:49], v[52:53]
	v_pk_mul_f32 v[38:39], v[38:39], v[62:63]
	v_pk_mul_f32 v[40:41], v[40:41], v[64:65]
	v_pk_mul_f32 v[46:47], v[42:43], v[46:47]
	v_pk_mul_f32 v[48:49], v[44:45], v[48:49]
	v_pk_mul_f32 v[38:39], v[34:35], v[38:39]
	v_pk_mul_f32 v[40:41], v[36:37], v[40:41]
	v_pk_add_f32 v[46:47], v[46:47], v[46:47] op_sel:[0,1] op_sel_hi:[0,1] neg_hi:[0,1]
	v_pk_add_f32 v[48:49], v[48:49], v[48:49] op_sel:[0,1] op_sel_hi:[0,1] neg_hi:[0,1]
	v_pk_add_f32 v[38:39], v[38:39], v[38:39] op_sel:[0,1] op_sel_hi:[0,1] neg_hi:[0,1]
	v_pk_add_f32 v[40:41], v[40:41], v[40:41] op_sel:[0,1] op_sel_hi:[0,1] neg_hi:[0,1]
	v_pk_add_f32 v[154:155], v[46:47], v[48:49] neg_lo:[0,1] neg_hi:[0,1]
	v_pk_add_f32 v[46:47], v[46:47], v[48:49]
	v_pk_add_f32 v[156:157], v[38:39], v[40:41] neg_lo:[0,1] neg_hi:[0,1]
	v_pk_add_f32 v[38:39], v[38:39], v[40:41]
	v_pk_add_f32 v[172:173], v[46:47], v[38:39] neg_lo:[0,1] neg_hi:[0,1]
	v_pk_add_f32 v[46:47], v[46:47], v[38:39]
	v_pk_add_f32 v[174:175], v[154:155], v[156:157] neg_lo:[0,1] neg_hi:[0,1]
	v_pk_add_f32 v[154:155], v[154:155], v[156:157]
	s_nop 1
	v_permlane16_swap_b32_e32 v46, v47
	v_permlane16_swap_b32_e32 v154, v155
	v_permlane16_swap_b32_e32 v172, v173
	v_permlane16_swap_b32_e32 v174, v175
	v_pk_add_f32 v[46:47], v[46:47], v[46:47] op_sel:[0,1] op_sel_hi:[0,1] neg_hi:[0,1]
	v_pk_add_f32 v[154:155], v[154:155], v[154:155] op_sel:[0,1] op_sel_hi:[0,1] neg_hi:[0,1]
	v_pk_add_f32 v[172:173], v[172:173], v[172:173] op_sel:[0,1] op_sel_hi:[0,1] neg_hi:[0,1]
	v_pk_add_f32 v[174:175], v[174:175], v[174:175] op_sel:[0,1] op_sel_hi:[0,1] neg_hi:[0,1]
	s_nop 0
	v_permlane16_swap_b32_e32 v46, v47
	v_permlane16_swap_b32_e32 v154, v155
	v_permlane16_swap_b32_e32 v172, v173
	v_permlane16_swap_b32_e32 v174, v175
	s_nop 1
	v_permlane32_swap_b32_e32 v46, v47
	v_permlane32_swap_b32_e32 v154, v155
	v_permlane32_swap_b32_e32 v172, v173
	v_permlane32_swap_b32_e32 v174, v175
	v_pk_add_f32 v[46:47], v[46:47], v[46:47] op_sel:[0,1] op_sel_hi:[0,1] neg_hi:[0,1]
	v_pk_add_f32 v[154:155], v[154:155], v[154:155] op_sel:[0,1] op_sel_hi:[0,1] neg_hi:[0,1]
	v_pk_add_f32 v[172:173], v[172:173], v[172:173] op_sel:[0,1] op_sel_hi:[0,1] neg_hi:[0,1]
	v_pk_add_f32 v[174:175], v[174:175], v[174:175] op_sel:[0,1] op_sel_hi:[0,1] neg_hi:[0,1]
	s_nop 0
	v_permlane32_swap_b32_e32 v46, v47
	v_permlane32_swap_b32_e32 v154, v155
	v_permlane32_swap_b32_e32 v172, v173
	v_permlane32_swap_b32_e32 v174, v175
	v_pk_mul_f32 v[46:47], v[46:47], v[246:247]
	v_pk_mul_f32 v[154:155], v[154:155], v[246:247]
	v_pk_mul_f32 v[172:173], v[172:173], v[246:247]
	v_pk_mul_f32 v[174:175], v[174:175], v[246:247]
	v_cvt_pk_bf16_f32 v168, v46, v47
	v_cvt_pk_bf16_f32 v169, v154, v155
	v_cvt_pk_bf16_f32 v170, v172, v173
	v_cvt_pk_bf16_f32 v171, v174, v175
	s_add_u32 s100, s98, 0x306000
	s_addc_u32 s101, s99, 0
	global_store_dwordx4 v250, v[168:171], s[100:101] nt
	v_pk_mul_f32 v[50:51], v[180:181], v[240:241] op_sel_hi:[1,0]
	v_pk_mul_f32 v[52:53], v[182:183], v[240:241] op_sel_hi:[1,0]
	v_pk_mul_f32 v[62:63], v[184:185], v[240:241] op_sel_hi:[1,0]
	v_pk_mul_f32 v[64:65], v[186:187], v[240:241] op_sel_hi:[1,0]
	v_pk_mul_f32 v[30:31], v[30:31], v[50:51]
	v_pk_mul_f32 v[32:33], v[32:33], v[52:53]
	v_pk_mul_f32 v[22:23], v[22:23], v[62:63]
	v_pk_mul_f32 v[24:25], v[24:25], v[64:65]
	v_pk_mul_f32 v[50:51], v[188:189], v[240:241] op_sel_hi:[1,0]
	v_pk_mul_f32 v[52:53], v[190:191], v[240:241] op_sel_hi:[1,0]
	v_pk_mul_f32 v[62:63], v[192:193], v[240:241] op_sel_hi:[1,0]
	v_pk_mul_f32 v[64:65], v[194:195], v[240:241] op_sel_hi:[1,0]
	v_pk_mul_f32 v[26:27], v[26:27], v[50:51]
	v_pk_mul_f32 v[28:29], v[28:29], v[52:53]
	v_pk_mul_f32 v[18:19], v[18:19], v[62:63]
	v_pk_mul_f32 v[20:21], v[20:21], v[64:65]
	v_pk_mul_f32 v[50:51], v[30:31], v[244:245]
	v_pk_mul_f32 v[52:53], v[32:33], v[244:245]
	v_pk_mul_f32 v[62:63], v[22:23], v[244:245]
	v_pk_mul_f32 v[64:65], v[24:25], v[244:245]
	v_exp_f32_e32 v50, v50
	v_exp_f32_e32 v51, v51
	v_exp_f32_e32 v52, v52
	v_exp_f32_e32 v53, v53
	v_exp_f32_e32 v62, v62
	v_exp_f32_e32 v63, v63
	v_exp_f32_e32 v64, v64
	v_exp_f32_e32 v65, v65
	v_pk_add_f32 v[50:51], v[50:51], v[248:249]
	v_pk_add_f32 v[52:53], v[52:53], v[248:249]
	v_pk_add_f32 v[62:63], v[62:63], v[248:249]
	v_pk_add_f32 v[64:65], v[64:65], v[248:249]
	v_rcp_f32_e32 v50, v50
	v_rcp_f32_e32 v51, v51
	v_rcp_f32_e32 v52, v52
	v_rcp_f32_e32 v53, v53
	v_rcp_f32_e32 v62, v62
	v_rcp_f32_e32 v63, v63
	v_rcp_f32_e32 v64, v64
	v_rcp_f32_e32 v65, v65
	v_pk_mul_f32 v[30:31], v[30:31], v[50:51]
	v_pk_mul_f32 v[32:33], v[32:33], v[52:53]
	v_pk_mul_f32 v[22:23], v[22:23], v[62:63]
	v_pk_mul_f32 v[24:25], v[24:25], v[64:65]
	v_pk_mul_f32 v[30:31], v[26:27], v[30:31]
	v_pk_mul_f32 v[32:33], v[28:29], v[32:33]
	v_pk_mul_f32 v[22:23], v[18:19], v[22:23]
	v_pk_mul_f32 v[24:25], v[20:21], v[24:25]
	v_pk_add_f32 v[30:31], v[30:31], v[30:31] op_sel:[0,1] op_sel_hi:[0,1] neg_hi:[0,1]
	v_pk_add_f32 v[32:33], v[32:33], v[32:33] op_sel:[0,1] op_sel_hi:[0,1] neg_hi:[0,1]
	v_pk_add_f32 v[22:23], v[22:23], v[22:23] op_sel:[0,1] op_sel_hi:[0,1] neg_hi:[0,1]
	v_pk_add_f32 v[24:25], v[24:25], v[24:25] op_sel:[0,1] op_sel_hi:[0,1] neg_hi:[0,1]
	v_pk_add_f32 v[154:155], v[30:31], v[32:33] neg_lo:[0,1] neg_hi:[0,1]
	v_pk_add_f32 v[30:31], v[30:31], v[32:33]
	v_pk_add_f32 v[156:157], v[22:23], v[24:25] neg_lo:[0,1] neg_hi:[0,1]
	v_pk_add_f32 v[22:23], v[22:23], v[24:25]
	v_pk_add_f32 v[172:173], v[30:31], v[22:23] neg_lo:[0,1] neg_hi:[0,1]
	v_pk_add_f32 v[30:31], v[30:31], v[22:23]
	v_pk_add_f32 v[174:175], v[154:155], v[156:157] neg_lo:[0,1] neg_hi:[0,1]
	v_pk_add_f32 v[154:155], v[154:155], v[156:157]
	s_nop 1
	v_permlane16_swap_b32_e32 v30, v31
	v_permlane16_swap_b32_e32 v154, v155
	v_permlane16_swap_b32_e32 v172, v173
	v_permlane16_swap_b32_e32 v174, v175
	v_pk_add_f32 v[30:31], v[30:31], v[30:31] op_sel:[0,1] op_sel_hi:[0,1] neg_hi:[0,1]
	v_pk_add_f32 v[154:155], v[154:155], v[154:155] op_sel:[0,1] op_sel_hi:[0,1] neg_hi:[0,1]
	v_pk_add_f32 v[172:173], v[172:173], v[172:173] op_sel:[0,1] op_sel_hi:[0,1] neg_hi:[0,1]
	v_pk_add_f32 v[174:175], v[174:175], v[174:175] op_sel:[0,1] op_sel_hi:[0,1] neg_hi:[0,1]
	s_nop 0
	v_permlane16_swap_b32_e32 v30, v31
	v_permlane16_swap_b32_e32 v154, v155
	v_permlane16_swap_b32_e32 v172, v173
	v_permlane16_swap_b32_e32 v174, v175
	s_nop 1
	v_permlane32_swap_b32_e32 v30, v31
	v_permlane32_swap_b32_e32 v154, v155
	v_permlane32_swap_b32_e32 v172, v173
	v_permlane32_swap_b32_e32 v174, v175
	v_pk_add_f32 v[30:31], v[30:31], v[30:31] op_sel:[0,1] op_sel_hi:[0,1] neg_hi:[0,1]
	v_pk_add_f32 v[154:155], v[154:155], v[154:155] op_sel:[0,1] op_sel_hi:[0,1] neg_hi:[0,1]
	v_pk_add_f32 v[172:173], v[172:173], v[172:173] op_sel:[0,1] op_sel_hi:[0,1] neg_hi:[0,1]
	v_pk_add_f32 v[174:175], v[174:175], v[174:175] op_sel:[0,1] op_sel_hi:[0,1] neg_hi:[0,1]
	s_nop 0
	v_permlane32_swap_b32_e32 v30, v31
	v_permlane32_swap_b32_e32 v154, v155
	v_permlane32_swap_b32_e32 v172, v173
	v_permlane32_swap_b32_e32 v174, v175
	v_pk_mul_f32 v[30:31], v[30:31], v[246:247]
	v_pk_mul_f32 v[154:155], v[154:155], v[246:247]
	v_pk_mul_f32 v[172:173], v[172:173], v[246:247]
	v_pk_mul_f32 v[174:175], v[174:175], v[246:247]
	v_cvt_pk_bf16_f32 v168, v30, v31
	v_cvt_pk_bf16_f32 v169, v154, v155
	v_cvt_pk_bf16_f32 v170, v172, v173
	v_cvt_pk_bf16_f32 v171, v174, v175
	s_add_u32 s100, s98, 0x35c000
	s_addc_u32 s101, s99, 0
	global_store_dwordx4 v250, v[168:171], s[100:101] nt
	v_pk_mul_f32 v[50:51], v[180:181], v[242:243] op_sel_hi:[1,0]
	v_pk_mul_f32 v[52:53], v[182:183], v[242:243] op_sel_hi:[1,0]
	v_pk_mul_f32 v[62:63], v[184:185], v[242:243] op_sel_hi:[1,0]
	v_pk_mul_f32 v[64:65], v[186:187], v[242:243] op_sel_hi:[1,0]
	v_pk_mul_f32 v[14:15], v[14:15], v[50:51]
	v_pk_mul_f32 v[16:17], v[16:17], v[52:53]
	v_pk_mul_f32 v[6:7], v[6:7], v[62:63]
	v_pk_mul_f32 v[8:9], v[8:9], v[64:65]
	v_pk_mul_f32 v[50:51], v[188:189], v[242:243] op_sel_hi:[1,0]
	v_pk_mul_f32 v[52:53], v[190:191], v[242:243] op_sel_hi:[1,0]
	v_pk_mul_f32 v[62:63], v[192:193], v[242:243] op_sel_hi:[1,0]
	v_pk_mul_f32 v[64:65], v[194:195], v[242:243] op_sel_hi:[1,0]
	v_pk_mul_f32 v[10:11], v[10:11], v[50:51]
	v_pk_mul_f32 v[12:13], v[12:13], v[52:53]
	v_pk_mul_f32 v[2:3], v[2:3], v[62:63]
	v_pk_mul_f32 v[4:5], v[4:5], v[64:65]
	v_pk_mul_f32 v[50:51], v[14:15], v[244:245]
	v_pk_mul_f32 v[52:53], v[16:17], v[244:245]
	v_pk_mul_f32 v[62:63], v[6:7], v[244:245]
	v_pk_mul_f32 v[64:65], v[8:9], v[244:245]
	v_exp_f32_e32 v50, v50
	v_exp_f32_e32 v51, v51
	v_exp_f32_e32 v52, v52
	v_exp_f32_e32 v53, v53
	v_exp_f32_e32 v62, v62
	v_exp_f32_e32 v63, v63
	v_exp_f32_e32 v64, v64
	v_exp_f32_e32 v65, v65
	v_pk_add_f32 v[50:51], v[50:51], v[248:249]
	v_pk_add_f32 v[52:53], v[52:53], v[248:249]
	v_pk_add_f32 v[62:63], v[62:63], v[248:249]
	v_pk_add_f32 v[64:65], v[64:65], v[248:249]
	v_rcp_f32_e32 v50, v50
	v_rcp_f32_e32 v51, v51
	v_rcp_f32_e32 v52, v52
	v_rcp_f32_e32 v53, v53
	v_rcp_f32_e32 v62, v62
	v_rcp_f32_e32 v63, v63
	v_rcp_f32_e32 v64, v64
	v_rcp_f32_e32 v65, v65
	v_pk_mul_f32 v[14:15], v[14:15], v[50:51]
	v_pk_mul_f32 v[16:17], v[16:17], v[52:53]
	v_pk_mul_f32 v[6:7], v[6:7], v[62:63]
	v_pk_mul_f32 v[8:9], v[8:9], v[64:65]
	v_pk_mul_f32 v[14:15], v[10:11], v[14:15]
	v_pk_mul_f32 v[16:17], v[12:13], v[16:17]
	v_pk_mul_f32 v[6:7], v[2:3], v[6:7]
	v_pk_mul_f32 v[8:9], v[4:5], v[8:9]
	v_pk_add_f32 v[14:15], v[14:15], v[14:15] op_sel:[0,1] op_sel_hi:[0,1] neg_hi:[0,1]
	v_pk_add_f32 v[16:17], v[16:17], v[16:17] op_sel:[0,1] op_sel_hi:[0,1] neg_hi:[0,1]
	v_pk_add_f32 v[6:7], v[6:7], v[6:7] op_sel:[0,1] op_sel_hi:[0,1] neg_hi:[0,1]
	v_pk_add_f32 v[8:9], v[8:9], v[8:9] op_sel:[0,1] op_sel_hi:[0,1] neg_hi:[0,1]
	v_pk_add_f32 v[154:155], v[14:15], v[16:17] neg_lo:[0,1] neg_hi:[0,1]
	v_pk_add_f32 v[14:15], v[14:15], v[16:17]
	v_pk_add_f32 v[156:157], v[6:7], v[8:9] neg_lo:[0,1] neg_hi:[0,1]
	v_pk_add_f32 v[6:7], v[6:7], v[8:9]
	v_pk_add_f32 v[172:173], v[14:15], v[6:7] neg_lo:[0,1] neg_hi:[0,1]
	v_pk_add_f32 v[14:15], v[14:15], v[6:7]
	v_pk_add_f32 v[174:175], v[154:155], v[156:157] neg_lo:[0,1] neg_hi:[0,1]
	v_pk_add_f32 v[154:155], v[154:155], v[156:157]
	s_nop 1
	v_permlane16_swap_b32_e32 v14, v15
	v_permlane16_swap_b32_e32 v154, v155
	v_permlane16_swap_b32_e32 v172, v173
	v_permlane16_swap_b32_e32 v174, v175
	v_pk_add_f32 v[14:15], v[14:15], v[14:15] op_sel:[0,1] op_sel_hi:[0,1] neg_hi:[0,1]
	v_pk_add_f32 v[154:155], v[154:155], v[154:155] op_sel:[0,1] op_sel_hi:[0,1] neg_hi:[0,1]
	v_pk_add_f32 v[172:173], v[172:173], v[172:173] op_sel:[0,1] op_sel_hi:[0,1] neg_hi:[0,1]
	v_pk_add_f32 v[174:175], v[174:175], v[174:175] op_sel:[0,1] op_sel_hi:[0,1] neg_hi:[0,1]
	s_nop 0
	v_permlane16_swap_b32_e32 v14, v15
	v_permlane16_swap_b32_e32 v154, v155
	v_permlane16_swap_b32_e32 v172, v173
	v_permlane16_swap_b32_e32 v174, v175
	s_nop 1
	v_permlane32_swap_b32_e32 v14, v15
	v_permlane32_swap_b32_e32 v154, v155
	v_permlane32_swap_b32_e32 v172, v173
	v_permlane32_swap_b32_e32 v174, v175
	v_pk_add_f32 v[14:15], v[14:15], v[14:15] op_sel:[0,1] op_sel_hi:[0,1] neg_hi:[0,1]
	v_pk_add_f32 v[154:155], v[154:155], v[154:155] op_sel:[0,1] op_sel_hi:[0,1] neg_hi:[0,1]
	v_pk_add_f32 v[172:173], v[172:173], v[172:173] op_sel:[0,1] op_sel_hi:[0,1] neg_hi:[0,1]
	v_pk_add_f32 v[174:175], v[174:175], v[174:175] op_sel:[0,1] op_sel_hi:[0,1] neg_hi:[0,1]
	s_nop 0
	v_permlane32_swap_b32_e32 v14, v15
	v_permlane32_swap_b32_e32 v154, v155
	v_permlane32_swap_b32_e32 v172, v173
	v_permlane32_swap_b32_e32 v174, v175
	v_pk_mul_f32 v[14:15], v[14:15], v[246:247]
	v_pk_mul_f32 v[154:155], v[154:155], v[246:247]
	v_pk_mul_f32 v[172:173], v[172:173], v[246:247]
	v_pk_mul_f32 v[174:175], v[174:175], v[246:247]
	v_cvt_pk_bf16_f32 v168, v14, v15
	v_cvt_pk_bf16_f32 v169, v154, v155
	v_cvt_pk_bf16_f32 v170, v172, v173
	v_cvt_pk_bf16_f32 v171, v174, v175
	s_add_u32 s100, s98, 0x3b2000
	s_addc_u32 s101, s99, 0
	global_store_dwordx4 v250, v[168:171], s[100:101] nt
	s_andn2_b64 vcc, exec, s[6:7]
	s_mov_b64 s[6:7], -1
	s_cbranch_vccnz .LBB0_907
	s_andn2_b64 vcc, exec, s[0:1]
	s_cbranch_vccnz .LBB0_906
	s_barrier
	s_branch .LBB0_906

.LBB0_918:
	s_cmpk_lg_i32 s94, 0x100
	s_cselect_b64 s[0:1], -1, 0
	s_cmpk_lt_i32 s62, 0xc0
	s_cselect_b64 s[2:3], -1, 0
	s_or_b64 s[0:1], s[2:3], s[0:1]
	s_and_b64 vcc, exec, s[0:1]
	s_cbranch_vccnz .LBB0_946
	s_add_i32 s100, s62, 0xffffff80
	s_waitcnt vmcnt(0) lgkmcnt(0)
	v_lshrrev_b32_e32 v1, 3, v178
	v_and_b32_e32 v2, 7, v178
	v_and_b32_e32 v3, 31, v178
	v_lshrrev_b32_e32 v175, 5, v178
	v_lshlrev_b32_e32 v176, 14, v1
	v_lshl_add_u32 v152, v2, 4, v176
	v_add_u32_e32 v153, 0x20000, v152
	v_add_u32_e32 v154, 0x40000, v152
	v_add_u32_e32 v155, 0x60000, v152
	v_add_u32_e32 v156, 0x80000, v152
	v_add_u32_e32 v157, 0xa0000, v152
	v_add_u32_e32 v158, 0xc0000, v152
	v_add_u32_e32 v159, 0xe0000, v152
	v_mul_u32_u24_e32 v172, 0x2b00, v3
	v_lshl_add_u32 v172, v175, 5, v172
	s_lshl_b32 s10, s92, 14
	v_mul_u32_u24_e32 v176, 0x84, v1
	v_lshl_add_u32 v176, v2, 4, v176
	v_add_u32_e32 v160, s10, v176
	v_add_u32_e32 v161, 0x420, v160
	v_add_u32_e32 v162, 0x840, v160
	v_add_u32_e32 v163, 0xc60, v160
	v_add_u32_e32 v164, 0x1080, v160
	v_add_u32_e32 v165, 0x14a0, v160
	v_add_u32_e32 v166, 0x18c0, v160
	v_add_u32_e32 v167, 0x1ce0, v160
	v_mul_u32_u24_e32 v176, 0x1080, v175
	v_lshl_add_u32 v176, v3, 2, v176
	v_add_u32_e32 v168, s10, v176
	v_add_u32_e32 v169, 0x420, v168
	v_add_u32_e32 v170, 0x840, v168
	v_add_u32_e32 v171, 0xc60, v168
	s_lshl_b32 s11, s92, 8
	v_lshl_add_u32 v177, v178, 2, s11
	v_add_u32_e32 v177, 0x3000, v177
	v_lshlrev_b32_e32 v176, 2, v3
	v_add_u32_e32 v1, 0x3000, v176
	s_lshl_b32 s10, s100, 7
	s_add_u32 s4, s48, s10
	s_addc_u32 s5, s49, 0
	s_mul_i32 s10, s100, 0x56000
	s_add_u32 s8, s54, s10
	s_addc_u32 s9, s55, 0
	s_add_u32 s8, s8, 0x13000000
	s_addc_u32 s9, s9, 0
	s_lshl_b32 s99, s100, 7
	v_mov_b32_e32 v173, 0
	s_mov_b32 s0, s92
	s_add_i32 s1, s0, 0
	s_lshl_b32 s10, s1, 20
	s_add_u32 s2, s4, s10
	s_addc_u32 s3, s5, 0
	global_load_dwordx4 v[4:7], v152, s[2:3]
	global_load_dwordx4 v[8:11], v153, s[2:3]
	global_load_dwordx4 v[12:15], v154, s[2:3]
	global_load_dwordx4 v[16:19], v155, s[2:3]
	global_load_dwordx4 v[20:23], v156, s[2:3]
	global_load_dwordx4 v[24:27], v157, s[2:3]
	global_load_dwordx4 v[28:31], v158, s[2:3]
	global_load_dwordx4 v[32:35], v159, s[2:3]
	s_add_i32 s1, s0, 8
	s_lshl_b32 s10, s1, 20
	s_add_u32 s2, s4, s10
	s_addc_u32 s3, s5, 0
	global_load_dwordx4 v[36:39], v152, s[2:3]
	global_load_dwordx4 v[40:43], v153, s[2:3]
	global_load_dwordx4 v[44:47], v154, s[2:3]
	global_load_dwordx4 v[48:51], v155, s[2:3]
	global_load_dwordx4 v[52:55], v156, s[2:3]
	global_load_dwordx4 v[56:59], v157, s[2:3]
	global_load_dwordx4 v[60:63], v158, s[2:3]
	global_load_dwordx4 v[64:67], v159, s[2:3]
	s_add_i32 s1, s0, 16
	s_lshl_b32 s10, s1, 20
	s_add_u32 s2, s4, s10
	s_addc_u32 s3, s5, 0
	global_load_dwordx4 v[68:71], v152, s[2:3]
	global_load_dwordx4 v[72:75], v153, s[2:3]
	global_load_dwordx4 v[76:79], v154, s[2:3]
	global_load_dwordx4 v[80:83], v155, s[2:3]
	global_load_dwordx4 v[84:87], v156, s[2:3]
	global_load_dwordx4 v[88:91], v157, s[2:3]
	global_load_dwordx4 v[92:95], v158, s[2:3]
	global_load_dwordx4 v[96:99], v159, s[2:3]

.Lqa_nosc3:
	s_mov_b32 s12, 0x0c0c0400
	s_mov_b32 s13, 0x05040100
	s_mov_b32 s98, 0x3e3504f3
	s_mov_b32 s99, 0x3e3504f3
	s_mov_b32 s100, 0x4b400000
	s_mov_b32 s101, 0x4b400000
	s_mov_b32 s0, s92
	s_add_i32 s1, s0, 0
	s_lshl_b32 s10, s1, 20
	s_add_u32 s2, s4, s10
	s_addc_u32 s3, s5, 0
	global_load_dwordx4 v[4:7], v152, s[2:3]
	global_load_dwordx4 v[8:11], v153, s[2:3]
	global_load_dwordx4 v[12:15], v154, s[2:3]
	global_load_dwordx4 v[16:19], v155, s[2:3]
	global_load_dwordx4 v[20:23], v156, s[2:3]
	global_load_dwordx4 v[24:27], v157, s[2:3]
	global_load_dwordx4 v[28:31], v158, s[2:3]
	global_load_dwordx4 v[32:35], v159, s[2:3]
	s_add_i32 s1, s0, 8
	s_lshl_b32 s10, s1, 20
	s_add_u32 s2, s4, s10
	s_addc_u32 s3, s5, 0
	global_load_dwordx4 v[36:39], v152, s[2:3]
	global_load_dwordx4 v[40:43], v153, s[2:3]
	global_load_dwordx4 v[44:47], v154, s[2:3]
	global_load_dwordx4 v[48:51], v155, s[2:3]
	global_load_dwordx4 v[52:55], v156, s[2:3]
	global_load_dwordx4 v[56:59], v157, s[2:3]
	global_load_dwordx4 v[60:63], v158, s[2:3]
	global_load_dwordx4 v[64:67], v159, s[2:3]
	s_add_i32 s1, s0, 16
	s_lshl_b32 s10, s1, 20
	s_add_u32 s2, s4, s10
	s_addc_u32 s3, s5, 0
	global_load_dwordx4 v[68:71], v152, s[2:3]
	global_load_dwordx4 v[72:75], v153, s[2:3]
	global_load_dwordx4 v[76:79], v154, s[2:3]
	global_load_dwordx4 v[80:83], v155, s[2:3]
	global_load_dwordx4 v[84:87], v156, s[2:3]
	global_load_dwordx4 v[88:91], v157, s[2:3]
	global_load_dwordx4 v[92:95], v158, s[2:3]
	global_load_dwordx4 v[96:99], v159, s[2:3]
